# P5 q/k epilogue: straight-line path for context tiles (no rope: x*C2 or new_k nt stores, bf16 pack), latent tiles keep the compiled path
# speedup vs baseline: 1.0042x; 1.0042x over previous
.LBB0_539:
	s_cmp_lt_u32 s27, 0x2000
	s_cbranch_scc0 .Lqkc_slow
	s_cmp_gt_i32 s10, 1
	s_cselect_b32 s9, 1, 0
	s_cselect_b32 s6, s46, s40
	s_cselect_b32 s7, s47, s41
	s_lshl_b32 s24, s10, 8
	s_and_b32 s24, s24, 0x100
	v_add_u32_e32 v130, s27, v167
	v_mov_b32_e32 v131, v143
	v_lshlrev_b64 v[132:133], 10, v[130:131]
	v_lshl_add_u64 v[132:133], s[6:7], 0, v[132:133]
	s_add_i32 s8, s24, s96
	v_add_lshl_u32 v134, v144, s8, 1
	v_mov_b32_e32 v135, v143
	v_lshl_add_u64 v[158:159], v[132:133], 0, v[134:135]
	v_lshlrev_b64 v[136:137], 11, v[130:131]
	v_lshl_add_u64 v[136:137], s[56:57], 0, v[136:137]
	v_add_lshl_u32 v134, v171, s24, 2
	v_lshl_add_u64 v[160:161], v[136:137], 0, v[134:135]
	s_mov_b64 s[76:77], 0x4000
	s_mov_b64 s[78:79], 0x8000
	s_mov_b64 s[80:81], 0x20000
	s_mov_b64 s[6:7], 0x40000
	s_cmp_eq_u32 s9, 1
	s_cbranch_scc1 .Lqkc_k
	v_lshl_add_u64 v[132:133], v[158:159], 0, 0
	v_pk_mul_f32 v[126:127], v[126:127], s[64:65] op_sel_hi:[1,0]
	v_pk_mul_f32 v[128:129], v[128:129], s[64:65] op_sel_hi:[1,0]
	v_pk_mul_f32 v[122:123], v[122:123], s[64:65] op_sel_hi:[1,0]
	v_pk_mul_f32 v[124:125], v[124:125], s[64:65] op_sel_hi:[1,0]
	v_cvt_pk_bf16_f32 v184, v126, v127
	v_cvt_pk_bf16_f32 v185, v128, v129
	v_cvt_pk_bf16_f32 v186, v122, v123
	v_cvt_pk_bf16_f32 v187, v124, v125
	global_store_dwordx4 v[132:133], v[184:187], off
	v_pk_mul_f32 v[118:119], v[118:119], s[64:65] op_sel_hi:[1,0]
	v_pk_mul_f32 v[120:121], v[120:121], s[64:65] op_sel_hi:[1,0]
	v_pk_mul_f32 v[114:115], v[114:115], s[64:65] op_sel_hi:[1,0]
	v_pk_mul_f32 v[116:117], v[116:117], s[64:65] op_sel_hi:[1,0]
	v_cvt_pk_bf16_f32 v188, v118, v119
	v_cvt_pk_bf16_f32 v189, v120, v121
	v_cvt_pk_bf16_f32 v190, v114, v115
	v_cvt_pk_bf16_f32 v191, v116, v117
	global_store_dwordx4 v[132:133], v[188:191], off offset:256
	v_lshl_add_u64 v[132:133], v[132:133], 0, s[76:77]
	v_pk_mul_f32 v[110:111], v[110:111], s[64:65] op_sel_hi:[1,0]
	v_pk_mul_f32 v[112:113], v[112:113], s[64:65] op_sel_hi:[1,0]
	v_pk_mul_f32 v[106:107], v[106:107], s[64:65] op_sel_hi:[1,0]
	v_pk_mul_f32 v[108:109], v[108:109], s[64:65] op_sel_hi:[1,0]
	v_cvt_pk_bf16_f32 v184, v110, v111
	v_cvt_pk_bf16_f32 v185, v112, v113
	v_cvt_pk_bf16_f32 v186, v106, v107
	v_cvt_pk_bf16_f32 v187, v108, v109
	global_store_dwordx4 v[132:133], v[184:187], off
	v_pk_mul_f32 v[102:103], v[102:103], s[64:65] op_sel_hi:[1,0]
	v_pk_mul_f32 v[104:105], v[104:105], s[64:65] op_sel_hi:[1,0]
	v_pk_mul_f32 v[98:99], v[98:99], s[64:65] op_sel_hi:[1,0]
	v_pk_mul_f32 v[100:101], v[100:101], s[64:65] op_sel_hi:[1,0]
	v_cvt_pk_bf16_f32 v188, v102, v103
	v_cvt_pk_bf16_f32 v189, v104, v105
	v_cvt_pk_bf16_f32 v190, v98, v99
	v_cvt_pk_bf16_f32 v191, v100, v101
	global_store_dwordx4 v[132:133], v[188:191], off offset:256
	v_lshl_add_u64 v[132:133], v[132:133], 0, s[76:77]
	v_pk_mul_f32 v[94:95], v[94:95], s[64:65] op_sel_hi:[1,0]
	v_pk_mul_f32 v[96:97], v[96:97], s[64:65] op_sel_hi:[1,0]
	v_pk_mul_f32 v[90:91], v[90:91], s[64:65] op_sel_hi:[1,0]
	v_pk_mul_f32 v[92:93], v[92:93], s[64:65] op_sel_hi:[1,0]
	v_cvt_pk_bf16_f32 v184, v94, v95
	v_cvt_pk_bf16_f32 v185, v96, v97
	v_cvt_pk_bf16_f32 v186, v90, v91
	v_cvt_pk_bf16_f32 v187, v92, v93
	global_store_dwordx4 v[132:133], v[184:187], off
	v_pk_mul_f32 v[86:87], v[86:87], s[64:65] op_sel_hi:[1,0]
	v_pk_mul_f32 v[88:89], v[88:89], s[64:65] op_sel_hi:[1,0]
	v_pk_mul_f32 v[82:83], v[82:83], s[64:65] op_sel_hi:[1,0]
	v_pk_mul_f32 v[84:85], v[84:85], s[64:65] op_sel_hi:[1,0]
	v_cvt_pk_bf16_f32 v188, v86, v87
	v_cvt_pk_bf16_f32 v189, v88, v89
	v_cvt_pk_bf16_f32 v190, v82, v83
	v_cvt_pk_bf16_f32 v191, v84, v85
	global_store_dwordx4 v[132:133], v[188:191], off offset:256
	v_lshl_add_u64 v[132:133], v[132:133], 0, s[76:77]
	v_pk_mul_f32 v[78:79], v[78:79], s[64:65] op_sel_hi:[1,0]
	v_pk_mul_f32 v[80:81], v[80:81], s[64:65] op_sel_hi:[1,0]
	v_pk_mul_f32 v[74:75], v[74:75], s[64:65] op_sel_hi:[1,0]
	v_pk_mul_f32 v[76:77], v[76:77], s[64:65] op_sel_hi:[1,0]
	v_cvt_pk_bf16_f32 v184, v78, v79
	v_cvt_pk_bf16_f32 v185, v80, v81
	v_cvt_pk_bf16_f32 v186, v74, v75
	v_cvt_pk_bf16_f32 v187, v76, v77
	global_store_dwordx4 v[132:133], v[184:187], off
	v_pk_mul_f32 v[70:71], v[70:71], s[64:65] op_sel_hi:[1,0]
	v_pk_mul_f32 v[72:73], v[72:73], s[64:65] op_sel_hi:[1,0]
	v_pk_mul_f32 v[66:67], v[66:67], s[64:65] op_sel_hi:[1,0]
	v_pk_mul_f32 v[68:69], v[68:69], s[64:65] op_sel_hi:[1,0]
	v_cvt_pk_bf16_f32 v188, v70, v71
	v_cvt_pk_bf16_f32 v189, v72, v73
	v_cvt_pk_bf16_f32 v190, v66, v67
	v_cvt_pk_bf16_f32 v191, v68, v69
	global_store_dwordx4 v[132:133], v[188:191], off offset:256
	v_lshl_add_u64 v[132:133], v[158:159], 0, s[80:81]
	v_pk_mul_f32 v[62:63], v[62:63], s[64:65] op_sel_hi:[1,0]
	v_pk_mul_f32 v[64:65], v[64:65], s[64:65] op_sel_hi:[1,0]
	v_pk_mul_f32 v[58:59], v[58:59], s[64:65] op_sel_hi:[1,0]
	v_pk_mul_f32 v[60:61], v[60:61], s[64:65] op_sel_hi:[1,0]
	v_cvt_pk_bf16_f32 v184, v62, v63
	v_cvt_pk_bf16_f32 v185, v64, v65
	v_cvt_pk_bf16_f32 v186, v58, v59
	v_cvt_pk_bf16_f32 v187, v60, v61
	global_store_dwordx4 v[132:133], v[184:187], off
	v_pk_mul_f32 v[54:55], v[54:55], s[64:65] op_sel_hi:[1,0]
	v_pk_mul_f32 v[56:57], v[56:57], s[64:65] op_sel_hi:[1,0]
	v_pk_mul_f32 v[50:51], v[50:51], s[64:65] op_sel_hi:[1,0]
	v_pk_mul_f32 v[52:53], v[52:53], s[64:65] op_sel_hi:[1,0]
	v_cvt_pk_bf16_f32 v188, v54, v55
	v_cvt_pk_bf16_f32 v189, v56, v57
	v_cvt_pk_bf16_f32 v190, v50, v51
	v_cvt_pk_bf16_f32 v191, v52, v53
	global_store_dwordx4 v[132:133], v[188:191], off offset:256
	v_lshl_add_u64 v[132:133], v[132:133], 0, s[76:77]
	v_pk_mul_f32 v[46:47], v[46:47], s[64:65] op_sel_hi:[1,0]
	v_pk_mul_f32 v[48:49], v[48:49], s[64:65] op_sel_hi:[1,0]
	v_pk_mul_f32 v[42:43], v[42:43], s[64:65] op_sel_hi:[1,0]
	v_pk_mul_f32 v[44:45], v[44:45], s[64:65] op_sel_hi:[1,0]
	v_cvt_pk_bf16_f32 v184, v46, v47
	v_cvt_pk_bf16_f32 v185, v48, v49
	v_cvt_pk_bf16_f32 v186, v42, v43
	v_cvt_pk_bf16_f32 v187, v44, v45
	global_store_dwordx4 v[132:133], v[184:187], off
	v_pk_mul_f32 v[38:39], v[38:39], s[64:65] op_sel_hi:[1,0]
	v_pk_mul_f32 v[40:41], v[40:41], s[64:65] op_sel_hi:[1,0]
	v_pk_mul_f32 v[34:35], v[34:35], s[64:65] op_sel_hi:[1,0]
	v_pk_mul_f32 v[36:37], v[36:37], s[64:65] op_sel_hi:[1,0]
	v_cvt_pk_bf16_f32 v188, v38, v39
	v_cvt_pk_bf16_f32 v189, v40, v41
	v_cvt_pk_bf16_f32 v190, v34, v35
	v_cvt_pk_bf16_f32 v191, v36, v37
	global_store_dwordx4 v[132:133], v[188:191], off offset:256
	v_lshl_add_u64 v[132:133], v[132:133], 0, s[76:77]
	v_pk_mul_f32 v[30:31], v[30:31], s[64:65] op_sel_hi:[1,0]
	v_pk_mul_f32 v[32:33], v[32:33], s[64:65] op_sel_hi:[1,0]
	v_pk_mul_f32 v[26:27], v[26:27], s[64:65] op_sel_hi:[1,0]
	v_pk_mul_f32 v[28:29], v[28:29], s[64:65] op_sel_hi:[1,0]
	v_cvt_pk_bf16_f32 v184, v30, v31
	v_cvt_pk_bf16_f32 v185, v32, v33
	v_cvt_pk_bf16_f32 v186, v26, v27
	v_cvt_pk_bf16_f32 v187, v28, v29
	global_store_dwordx4 v[132:133], v[184:187], off
	v_pk_mul_f32 v[22:23], v[22:23], s[64:65] op_sel_hi:[1,0]
	v_pk_mul_f32 v[24:25], v[24:25], s[64:65] op_sel_hi:[1,0]
	v_pk_mul_f32 v[18:19], v[18:19], s[64:65] op_sel_hi:[1,0]
	v_pk_mul_f32 v[20:21], v[20:21], s[64:65] op_sel_hi:[1,0]
	v_cvt_pk_bf16_f32 v188, v22, v23
	v_cvt_pk_bf16_f32 v189, v24, v25
	v_cvt_pk_bf16_f32 v190, v18, v19
	v_cvt_pk_bf16_f32 v191, v20, v21
	global_store_dwordx4 v[132:133], v[188:191], off offset:256
	v_lshl_add_u64 v[132:133], v[132:133], 0, s[76:77]
	v_pk_mul_f32 v[14:15], v[14:15], s[64:65] op_sel_hi:[1,0]
	v_pk_mul_f32 v[16:17], v[16:17], s[64:65] op_sel_hi:[1,0]
	v_pk_mul_f32 v[10:11], v[10:11], s[64:65] op_sel_hi:[1,0]
	v_pk_mul_f32 v[12:13], v[12:13], s[64:65] op_sel_hi:[1,0]
	v_cvt_pk_bf16_f32 v184, v14, v15
	v_cvt_pk_bf16_f32 v185, v16, v17
	v_cvt_pk_bf16_f32 v186, v10, v11
	v_cvt_pk_bf16_f32 v187, v12, v13
	global_store_dwordx4 v[132:133], v[184:187], off
	v_pk_mul_f32 v[6:7], v[6:7], s[64:65] op_sel_hi:[1,0]
	v_pk_mul_f32 v[8:9], v[8:9], s[64:65] op_sel_hi:[1,0]
	v_pk_mul_f32 v[2:3], v[2:3], s[64:65] op_sel_hi:[1,0]
	v_pk_mul_f32 v[4:5], v[4:5], s[64:65] op_sel_hi:[1,0]
	v_cvt_pk_bf16_f32 v188, v6, v7
	v_cvt_pk_bf16_f32 v189, v8, v9
	v_cvt_pk_bf16_f32 v190, v2, v3
	v_cvt_pk_bf16_f32 v191, v4, v5
	global_store_dwordx4 v[132:133], v[188:191], off offset:256
	s_branch .LBB0_537
.Lqkc_k:
	v_lshl_add_u64 v[132:133], v[158:159], 0, 0
	v_lshl_add_u64 v[136:137], v[160:161], 0, 0
	global_store_dwordx4 v[136:137], v[126:129], off nt
	global_store_dwordx4 v[136:137], v[122:125], off offset:64 nt
	v_cvt_pk_bf16_f32 v184, v126, v127
	v_cvt_pk_bf16_f32 v185, v128, v129
	v_cvt_pk_bf16_f32 v186, v122, v123
	v_cvt_pk_bf16_f32 v187, v124, v125
	global_store_dwordx4 v[132:133], v[184:187], off
	global_store_dwordx4 v[136:137], v[118:121], off offset:512 nt
	global_store_dwordx4 v[136:137], v[114:117], off offset:576 nt
	v_cvt_pk_bf16_f32 v188, v118, v119
	v_cvt_pk_bf16_f32 v189, v120, v121
	v_cvt_pk_bf16_f32 v190, v114, v115
	v_cvt_pk_bf16_f32 v191, v116, v117
	global_store_dwordx4 v[132:133], v[188:191], off offset:256
	v_lshl_add_u64 v[132:133], v[132:133], 0, s[76:77]
	v_lshl_add_u64 v[136:137], v[136:137], 0, s[78:79]
	global_store_dwordx4 v[136:137], v[110:113], off nt
	global_store_dwordx4 v[136:137], v[106:109], off offset:64 nt
	v_cvt_pk_bf16_f32 v184, v110, v111
	v_cvt_pk_bf16_f32 v185, v112, v113
	v_cvt_pk_bf16_f32 v186, v106, v107
	v_cvt_pk_bf16_f32 v187, v108, v109
	global_store_dwordx4 v[132:133], v[184:187], off
	global_store_dwordx4 v[136:137], v[102:105], off offset:512 nt
	global_store_dwordx4 v[136:137], v[98:101], off offset:576 nt
	v_cvt_pk_bf16_f32 v188, v102, v103
	v_cvt_pk_bf16_f32 v189, v104, v105
	v_cvt_pk_bf16_f32 v190, v98, v99
	v_cvt_pk_bf16_f32 v191, v100, v101
	global_store_dwordx4 v[132:133], v[188:191], off offset:256
	v_lshl_add_u64 v[132:133], v[132:133], 0, s[76:77]
	v_lshl_add_u64 v[136:137], v[136:137], 0, s[78:79]
	global_store_dwordx4 v[136:137], v[94:97], off nt
	global_store_dwordx4 v[136:137], v[90:93], off offset:64 nt
	v_cvt_pk_bf16_f32 v184, v94, v95
	v_cvt_pk_bf16_f32 v185, v96, v97
	v_cvt_pk_bf16_f32 v186, v90, v91
	v_cvt_pk_bf16_f32 v187, v92, v93
	global_store_dwordx4 v[132:133], v[184:187], off
	global_store_dwordx4 v[136:137], v[86:89], off offset:512 nt
	global_store_dwordx4 v[136:137], v[82:85], off offset:576 nt
	v_cvt_pk_bf16_f32 v188, v86, v87
	v_cvt_pk_bf16_f32 v189, v88, v89
	v_cvt_pk_bf16_f32 v190, v82, v83
	v_cvt_pk_bf16_f32 v191, v84, v85
	global_store_dwordx4 v[132:133], v[188:191], off offset:256
	v_lshl_add_u64 v[132:133], v[132:133], 0, s[76:77]
	v_lshl_add_u64 v[136:137], v[136:137], 0, s[78:79]
	global_store_dwordx4 v[136:137], v[78:81], off nt
	global_store_dwordx4 v[136:137], v[74:77], off offset:64 nt
	v_cvt_pk_bf16_f32 v184, v78, v79
	v_cvt_pk_bf16_f32 v185, v80, v81
	v_cvt_pk_bf16_f32 v186, v74, v75
	v_cvt_pk_bf16_f32 v187, v76, v77
	global_store_dwordx4 v[132:133], v[184:187], off
	global_store_dwordx4 v[136:137], v[70:73], off offset:512 nt
	global_store_dwordx4 v[136:137], v[66:69], off offset:576 nt
	v_cvt_pk_bf16_f32 v188, v70, v71
	v_cvt_pk_bf16_f32 v189, v72, v73
	v_cvt_pk_bf16_f32 v190, v66, v67
	v_cvt_pk_bf16_f32 v191, v68, v69
	global_store_dwordx4 v[132:133], v[188:191], off offset:256
	v_lshl_add_u64 v[132:133], v[158:159], 0, s[80:81]
	v_lshl_add_u64 v[136:137], v[160:161], 0, s[6:7]
	global_store_dwordx4 v[136:137], v[62:65], off nt
	global_store_dwordx4 v[136:137], v[58:61], off offset:64 nt
	v_cvt_pk_bf16_f32 v184, v62, v63
	v_cvt_pk_bf16_f32 v185, v64, v65
	v_cvt_pk_bf16_f32 v186, v58, v59
	v_cvt_pk_bf16_f32 v187, v60, v61
	global_store_dwordx4 v[132:133], v[184:187], off
	global_store_dwordx4 v[136:137], v[54:57], off offset:512 nt
	global_store_dwordx4 v[136:137], v[50:53], off offset:576 nt
	v_cvt_pk_bf16_f32 v188, v54, v55
	v_cvt_pk_bf16_f32 v189, v56, v57
	v_cvt_pk_bf16_f32 v190, v50, v51
	v_cvt_pk_bf16_f32 v191, v52, v53
	global_store_dwordx4 v[132:133], v[188:191], off offset:256
	v_lshl_add_u64 v[132:133], v[132:133], 0, s[76:77]
	v_lshl_add_u64 v[136:137], v[136:137], 0, s[78:79]
	global_store_dwordx4 v[136:137], v[46:49], off nt
	global_store_dwordx4 v[136:137], v[42:45], off offset:64 nt
	v_cvt_pk_bf16_f32 v184, v46, v47
	v_cvt_pk_bf16_f32 v185, v48, v49
	v_cvt_pk_bf16_f32 v186, v42, v43
	v_cvt_pk_bf16_f32 v187, v44, v45
	global_store_dwordx4 v[132:133], v[184:187], off
	global_store_dwordx4 v[136:137], v[38:41], off offset:512 nt
	global_store_dwordx4 v[136:137], v[34:37], off offset:576 nt
	v_cvt_pk_bf16_f32 v188, v38, v39
	v_cvt_pk_bf16_f32 v189, v40, v41
	v_cvt_pk_bf16_f32 v190, v34, v35
	v_cvt_pk_bf16_f32 v191, v36, v37
	global_store_dwordx4 v[132:133], v[188:191], off offset:256
	v_lshl_add_u64 v[132:133], v[132:133], 0, s[76:77]
	v_lshl_add_u64 v[136:137], v[136:137], 0, s[78:79]
	global_store_dwordx4 v[136:137], v[30:33], off nt
	global_store_dwordx4 v[136:137], v[26:29], off offset:64 nt
	v_cvt_pk_bf16_f32 v184, v30, v31
	v_cvt_pk_bf16_f32 v185, v32, v33
	v_cvt_pk_bf16_f32 v186, v26, v27
	v_cvt_pk_bf16_f32 v187, v28, v29
	global_store_dwordx4 v[132:133], v[184:187], off
	global_store_dwordx4 v[136:137], v[22:25], off offset:512 nt
	global_store_dwordx4 v[136:137], v[18:21], off offset:576 nt
	v_cvt_pk_bf16_f32 v188, v22, v23
	v_cvt_pk_bf16_f32 v189, v24, v25
	v_cvt_pk_bf16_f32 v190, v18, v19
	v_cvt_pk_bf16_f32 v191, v20, v21
	global_store_dwordx4 v[132:133], v[188:191], off offset:256
	v_lshl_add_u64 v[132:133], v[132:133], 0, s[76:77]
	v_lshl_add_u64 v[136:137], v[136:137], 0, s[78:79]
	global_store_dwordx4 v[136:137], v[14:17], off nt
	global_store_dwordx4 v[136:137], v[10:13], off offset:64 nt
	v_cvt_pk_bf16_f32 v184, v14, v15
	v_cvt_pk_bf16_f32 v185, v16, v17
	v_cvt_pk_bf16_f32 v186, v10, v11
	v_cvt_pk_bf16_f32 v187, v12, v13
	global_store_dwordx4 v[132:133], v[184:187], off
	global_store_dwordx4 v[136:137], v[6:9], off offset:512 nt
	global_store_dwordx4 v[136:137], v[2:5], off offset:576 nt
	v_cvt_pk_bf16_f32 v188, v6, v7
	v_cvt_pk_bf16_f32 v189, v8, v9
	v_cvt_pk_bf16_f32 v190, v2, v3
	v_cvt_pk_bf16_f32 v191, v4, v5
	global_store_dwordx4 v[132:133], v[188:191], off offset:256
	s_branch .LBB0_537
